# diff_attn main loop: PV half-1 V-fragment LDS reads batched (8 quads), next-tile LDS writes issued before the MFMAs (stacked on v7)
# speedup vs baseline: 1.0077x; 1.0049x over previous
; DI void diff_attn_phase(int wv, LAS unsigned char* lds, const bf16_t* qk, const bf16_t* vt, bf16_t* ob, const float* lq1, const float* lk1, const float* lq2, const float* lk2,
;                         const float* subg, int layer_idx) {
;     ...
;         for (int t = 0; t < tmain; ++t) {
;             const int key0 = t * 64;
;             const bool more = true;
;             if (more) {
; #pragma unroll
;                 for (int i = 0; i < 2; ++i) gk[i] = *(const u32x4*)(kg + (size_t)(key0 + 64 + i * 32) * 2048); }
;             LAS unsigned char* buf = lds + (t & 1) * DA_BUF;
;             {
;                 f32x16 S0 = zero16(), S1 = zero16();
;                 {
;                     bf16x8 kf[2][4];
; #pragma unroll
;                     for (int sub = 0; sub < 2; ++sub)
; #pragma unroll
;                         for (int ks = 0; ks < 4; ++ks) kf[sub][ks] = *(const LAS bf16x8*)(buf + koff + sub * 32 * DA_KP + ks * 32);
; #pragma unroll
;                     for (int ks = 0; ks < 4; ++ks) { const bf16x8 qfr = *(const LAS bf16x8*)(qlds + ks * 1024); S0 = MFMA32(kf[0][ks], qfr, S0); S1 = MFMA32(kf[1][ks], qfr, S1); }
;                 }
;                 __builtin_amdgcn_sched_barrier(0);
; #pragma unroll
;                 for (int i = 0; i < 2; ++i) gv[i] = *(const u32x4*)(vg + (size_t)i * 64 * M_TOK + key0 + 64);
;                 bf16x8 vf[4][2];
; #pragma unroll
;                 for (int d = 0; d < 4; ++d)
; #pragma unroll
;                     for (int s2 = 0; s2 < 2; ++s2) vf[d][s2] = *(const LAS bf16x8*)(buf + voff + d * 32 * DA_VP + (16 * s2) * 2);
;                 const float base = slope2 * (float)(key0 + 8 * hh - qpos), b32 = 32.f * slope2;
; #pragma unroll
;                 for (int i = 0; i < 16; ++i) { S0[i] = S0[i] * c1 + cb[i]; S1[i] = S1[i] * c1 + cb[i]; }
;                 float mx = -INFINITY, mx1 = -INFINITY;
; #pragma unroll
;                 for (int i = 0; i < 16; ++i) { mx = fmaxf(mx, S0[i]); mx1 = fmaxf(mx1, S1[i]); }
;                 mx = fmaxf(mx, mx1 + b32) + base;
;                 mx = fmaxf(mx, __shfl_xor(mx, 32));
;                 {
;                     const float mn = fmaxf(m, mx), alpha = fexp2(m - mn); m = mn; l *= alpha;
; #pragma unroll
;                     for (int d = 0; d < 4; ++d) O[d] = O[d] * alpha;
;                 }
;                 const float off = base - m, off1 = off + b32;
.LBB0_424:
	s_add_i32 s14, s16, 64
	s_ashr_i32 s15, s14, 31
	s_lshl_b64 s[26:27], s[14:15], 12
	v_lshl_add_u64 v[66:67], v[114:115], 0, s[26:27]
	s_add_i32 s26, s16, 0x60
	s_ashr_i32 s27, s26, 31
	s_lshl_b64 s[26:27], s[26:27], 12
	global_load_dwordx4 v[98:101], v[66:67], off offset:2048
	v_lshl_add_u64 v[66:67], v[114:115], 0, s[26:27]
	global_load_dwordx4 v[102:105], v[66:67], off offset:2048
	s_bitcmp1_b32 s25, 0
	s_cselect_b32 s2, 0x8c00, 0
	s_add_i32 s2, s2, 0
	v_add_u32_e32 v70, s2, v153
	ds_read_b128 v[66:69], v70
	ds_read_b128 v[82:85], v70 offset:32
	ds_read_b128 v[86:89], v70 offset:64
	ds_read_b128 v[90:93], v70 offset:96
	ds_read_b128 v[94:97], v70 offset:8704
	ds_read_b128 v[106:109], v70 offset:8736
	ds_read_b128 v[110:113], v70 offset:8768
	ds_read_b128 v[122:125], v70 offset:8800
	ds_read_b128 v[126:129], v217
	ds_read_b128 v[130:133], v217 offset:1024
	ds_read_b128 v[134:137], v217 offset:2048
	ds_read_b128 v[138:141], v217 offset:3072
	v_mov_b32_e32 v121, v159
	v_mov_b32_e32 v0, v218
	s_waitcnt lgkmcnt(3)
	v_mfma_f32_32x32x16_bf16 v[66:81], v[66:69], v[126:129], 0
	s_ashr_i32 s17, s16, 31
	s_mov_b32 s3, 0x400000
	v_add_u32_e32 v118, s16, v120
	v_add_u32_e32 v191, s2, v211
	s_waitcnt lgkmcnt(2)
	v_mfma_f32_32x32x16_bf16 v[66:81], v[82:85], v[130:133], v[66:81]
	s_waitcnt lgkmcnt(1)
	v_mfma_f32_32x32x16_bf16 v[66:81], v[86:89], v[134:137], v[66:81]
	s_waitcnt lgkmcnt(0)
	v_mfma_f32_32x32x16_bf16 v[66:81], v[90:93], v[138:141], v[66:81]
	v_mfma_f32_32x32x16_bf16 v[82:97], v[94:97], v[126:129], 0
	s_nop 10
	v_fmamk_f32 v127, v66, 0x3e38aa3b, v192
	v_max_f32_e32 v66, 0xff800000, v127
	v_fmamk_f32 v129, v69, 0x3e38aa3b, v189
	v_fmamk_f32 v159, v74, 0x3e38aa3b, v182
	v_fmamk_f32 v193, v75, 0x3e38aa3b, v183
	v_fmamk_f32 v196, v76, 0x3e38aa3b, v180
	v_cvt_f32_i32_e32 v126, v118
	v_mfma_f32_32x32x16_bf16 v[82:97], v[106:109], v[130:133], v[82:97]
	v_lshl_add_u64 v[106:107], s[16:17], 1, v[116:117]
	v_add_co_u32_e32 v108, vcc, s3, v106
	v_fmamk_f32 v131, v70, 0x3e38aa3b, v186
	s_nop 0
	v_addc_co_u32_e32 v109, vcc, 0, v107, vcc
	v_fmamk_f32 v133, v71, 0x3e38aa3b, v187
	v_mfma_f32_32x32x16_bf16 v[82:97], v[110:113], v[134:137], v[82:97]
	global_load_dwordx4 v[110:113], v[106:107], off offset:128
	s_nop 0
	global_load_dwordx4 v[106:109], v[108:109], off offset:128
	v_fmamk_f32 v135, v72, 0x3e38aa3b, v184
	v_fmamk_f32 v137, v73, 0x3e38aa3b, v185
	v_fmamk_f32 v199, v77, 0x3e38aa3b, v181
	v_fmamk_f32 v200, v78, 0x3e38aa3b, v178
	v_fmamk_f32 v204, v79, 0x3e38aa3b, v179
	v_fmamk_f32 v207, v80, 0x3e38aa3b, v176
	v_mfma_f32_32x32x16_bf16 v[82:97], v[122:125], v[138:141], v[82:97]
	v_fmamk_f32 v123, v67, 0x3e38aa3b, v160
	v_fmamk_f32 v125, v68, 0x3e38aa3b, v188
	v_max3_f32 v66, v66, v123, v125
	v_max3_f32 v66, v66, v129, v131
	v_max3_f32 v66, v66, v133, v135
	v_max3_f32 v66, v66, v137, v159
	v_max3_f32 v66, v66, v193, v196
	s_nop 4
	v_fmamk_f32 v122, v82, 0x3e38aa3b, v192
	v_fmamk_f32 v124, v83, 0x3e38aa3b, v160
	v_fmamk_f32 v128, v84, 0x3e38aa3b, v188
	v_fmamk_f32 v130, v85, 0x3e38aa3b, v189
	v_max3_f32 v67, v122, s54, v124
	v_fmamk_f32 v132, v86, 0x3e38aa3b, v186
	v_fmamk_f32 v134, v87, 0x3e38aa3b, v187
	v_max3_f32 v67, v67, v128, v130
	v_fmamk_f32 v136, v88, 0x3e38aa3b, v184
	v_fmamk_f32 v143, v89, 0x3e38aa3b, v185
	v_max3_f32 v67, v67, v132, v134
	v_fmamk_f32 v169, v90, 0x3e38aa3b, v182
	v_fmamk_f32 v195, v91, 0x3e38aa3b, v183
	v_max3_f32 v67, v67, v136, v143
	v_fmamk_f32 v198, v92, 0x3e38aa3b, v180
	v_fmamk_f32 v202, v93, 0x3e38aa3b, v181
	v_max3_f32 v67, v67, v169, v195
	v_fmamk_f32 v203, v94, 0x3e38aa3b, v178
	v_fmamk_f32 v206, v95, 0x3e38aa3b, v179
	v_max3_f32 v67, v67, v198, v202
	v_fmamk_f32 v219, v96, 0x3e38aa3b, v176
	v_fmamk_f32 v222, v97, 0x3e38aa3b, v177
	v_max3_f32 v67, v67, v203, v206
	v_max3_f32 v66, v66, v199, v200
	v_max3_f32 v67, v67, v219, v222
	v_fmamk_f32 v220, v81, 0x3e38aa3b, v177
	v_max3_f32 v66, v66, v204, v207
	v_add_f32_e32 v67, v157, v67
	v_max3_f32 v66, v66, v220, v67
	v_fmac_f32_e32 v66, v160, v126
	ds_bpermute_b32 v67, v238, v66
	ds_read_b128 v[94:97], v191 offset:17408
	ds_read_b128 v[90:93], v191 offset:17440
	ds_read_b128 v[86:89], v191 offset:22016
	ds_read_b128 v[82:85], v191 offset:22048
	s_waitcnt lgkmcnt(4)
	v_max3_f32 v218, v0, v66, v67
	v_sub_f32_e32 v0, v0, v218
	v_fma_f32 v126, v160, v126, -v218
	v_exp_f32_e32 v118, v0
	v_add_f32_e32 v223, v157, v126
	v_add_f32_e32 v0, v127, v126
	v_exp_f32_e32 v127, v0
	v_add_f32_e32 v0, v122, v223
	v_add_f32_e32 v122, v125, v126
	v_exp_f32_e32 v224, v0
	v_add_f32_e32 v0, v123, v126
	v_exp_f32_e32 v123, v122
	v_add_f32_e32 v122, v128, v223
	v_exp_f32_e32 v225, v122
	v_add_f32_e32 v122, v129, v126
	v_exp_f32_e32 v140, v122
	v_add_f32_e32 v122, v130, v223
	v_exp_f32_e32 v142, v122
	v_add_f32_e32 v122, v133, v126
	v_exp_f32_e32 v144, v122
	v_add_f32_e32 v122, v134, v223
	v_exp_f32_e32 v168, v122
	v_add_f32_e32 v122, v137, v126
	v_exp_f32_e32 v170, v122
	v_add_f32_e32 v122, v143, v223
	v_add_f32_e32 v129, v169, v223
	v_exp_f32_e32 v194, v122
	v_add_f32_e32 v122, v193, v126
	v_exp_f32_e32 v134, v129
	v_add_f32_e32 v129, v196, v126
	v_exp_f32_e32 v196, v122
	v_add_f32_e32 v122, v195, v223
	v_add_f32_e32 v125, v132, v223
	v_add_f32_e32 v130, v198, v223
	v_exp_f32_e32 v198, v122
	v_add_f32_e32 v122, v199, v126
	v_exp_f32_e32 v132, v125
	v_add_f32_e32 v125, v135, v126
	v_exp_f32_e32 v135, v130
	v_add_f32_e32 v130, v200, v126
	v_exp_f32_e32 v200, v122
	v_add_f32_e32 v122, v202, v223
	v_exp_f32_e32 v202, v122
	v_add_f32_e32 v122, v204, v126
	ds_read_b128 v[78:81], v191 offset:26624
	ds_read_b128 v[74:77], v191 offset:26656
	ds_read_b128 v[70:73], v191 offset:31232
; #define LAS __attribute__((address_space(3)))
; DI float fexp2(float x) { return __builtin_amdgcn_exp2f(x); }
; #define MFMA32(a, b, c) __builtin_amdgcn_mfma_f32_32x32x16_bf16((a), (b), (c), 0, 0, 0)
; DI void diff_attn_phase(int wv, LAS unsigned char* lds, const bf16_t* qk, const bf16_t* vt, bf16_t* ob, const float* lq1, const float* lk1, const float* lq2, const float* lk2,
;                         const float* subg, int layer_idx) {
;     ...
;                     for (int d = 0; d < 4; ++d) O[d] = O[d] * alpha;
;                 }
;                 const float off = base - m, off1 = off + b32;
;                 float ps = 0.f;
; #pragma unroll
;                 for (int i = 0; i < 16; ++i) { S0[i] = fexp2(S0[i] + off); S1[i] = fexp2(S1[i] + off1); ps += S0[i] + S1[i]; }
;                 l += ps;
;                 const bf16x8 p0 = pack8(S0, 0), p1 = pack8(S0, 1), p2 = pack8(S1, 0), p3 = pack8(S1, 1);
;                 __builtin_amdgcn_sched_barrier(0);
; #pragma unroll
;                 for (int d = 0; d < 4; ++d) { O[d] = MFMA32(vf[d][0], p0, O[d]); O[d] = MFMA32(vf[d][1], p1, O[d]); }
;                 __builtin_amdgcn_sched_barrier(0);
; #pragma unroll
;                 for (int d = 0; d < 4; ++d)
; #pragma unroll
;                     for (int s2 = 0; s2 < 2; ++s2) vf[d][s2] = *(const LAS bf16x8*)(buf + voff + d * 32 * DA_VP + (32 + 16 * s2) * 2);
; #pragma unroll
;                 for (int d = 0; d < 4; ++d) { O[d] = MFMA32(vf[d][0], p2, O[d]); O[d] = MFMA32(vf[d][1], p3, O[d]); }
;             }
;             if (more) {
;                 LAS unsigned char* nb = lds + ((t + 1) & 1) * DA_BUF;
; #pragma unroll
;                 for (int i = 0; i < 2; ++i) { *(LAS u32x4*)(nb + kst_off + i * 32 * DA_KP) = gk[i]; *(LAS u32x4*)(nb + vst_off + i * 64 * DA_VP) = gv[i]; } }
;             __syncthreads();
	ds_read_b128 v[66:69], v191 offset:31264
	v_exp_f32_e32 v204, v122
	v_add_f32_e32 v122, v206, v223
	v_exp_f32_e32 v138, v0
	v_add_f32_e32 v0, v124, v223
	v_add_f32_e32 v124, v131, v126
	v_add_f32_e32 v128, v136, v223
	v_add_f32_e32 v131, v203, v223
	v_exp_f32_e32 v206, v122
	v_add_f32_e32 v122, v220, v126
	v_exp_f32_e32 v133, v128
	v_add_f32_e32 v128, v159, v126
	v_exp_f32_e32 v136, v131
	v_add_f32_e32 v131, v207, v126
	v_add_f32_e32 v137, v219, v223
	v_exp_f32_e32 v220, v122
	v_add_f32_e32 v122, v222, v223
	v_exp_f32_e32 v0, v0
	v_exp_f32_e32 v124, v124
	v_exp_f32_e32 v125, v125
	v_exp_f32_e32 v128, v128
	v_exp_f32_e32 v129, v129
	v_exp_f32_e32 v130, v130
	v_exp_f32_e32 v131, v131
	v_exp_f32_e32 v137, v137
	v_exp_f32_e32 v222, v122
	v_pk_mul_f32 v[64:65], v[64:65], v[118:119] op_sel_hi:[1,0]
	v_pk_mul_f32 v[62:63], v[62:63], v[118:119] op_sel_hi:[1,0]
	v_pk_mul_f32 v[60:61], v[60:61], v[118:119] op_sel_hi:[1,0]
	v_pk_mul_f32 v[58:59], v[58:59], v[118:119] op_sel_hi:[1,0]
	v_pk_mul_f32 v[56:57], v[56:57], v[118:119] op_sel_hi:[1,0]
	v_pk_mul_f32 v[54:55], v[54:55], v[118:119] op_sel_hi:[1,0]
	v_pk_mul_f32 v[52:53], v[52:53], v[118:119] op_sel_hi:[1,0]
	v_pk_mul_f32 v[50:51], v[50:51], v[118:119] op_sel_hi:[1,0]
	v_pk_mul_f32 v[48:49], v[48:49], v[118:119] op_sel_hi:[1,0]
	v_pk_mul_f32 v[46:47], v[46:47], v[118:119] op_sel_hi:[1,0]
	v_pk_mul_f32 v[44:45], v[44:45], v[118:119] op_sel_hi:[1,0]
	v_pk_mul_f32 v[42:43], v[42:43], v[118:119] op_sel_hi:[1,0]
	v_pk_mul_f32 v[40:41], v[40:41], v[118:119] op_sel_hi:[1,0]
	v_pk_mul_f32 v[38:39], v[38:39], v[118:119] op_sel_hi:[1,0]
	v_pk_mul_f32 v[36:37], v[36:37], v[118:119] op_sel_hi:[1,0]
	v_pk_mul_f32 v[34:35], v[34:35], v[118:119] op_sel_hi:[1,0]
	v_pk_mul_f32 v[32:33], v[32:33], v[118:119] op_sel_hi:[1,0]
	v_pk_mul_f32 v[30:31], v[30:31], v[118:119] op_sel_hi:[1,0]
	v_pk_mul_f32 v[28:29], v[28:29], v[118:119] op_sel_hi:[1,0]
	v_pk_mul_f32 v[26:27], v[26:27], v[118:119] op_sel_hi:[1,0]
	v_pk_mul_f32 v[24:25], v[24:25], v[118:119] op_sel_hi:[1,0]
	v_pk_mul_f32 v[22:23], v[22:23], v[118:119] op_sel_hi:[1,0]
	v_pk_mul_f32 v[20:21], v[20:21], v[118:119] op_sel_hi:[1,0]
	v_pk_mul_f32 v[18:19], v[18:19], v[118:119] op_sel_hi:[1,0]
	v_pk_mul_f32 v[16:17], v[16:17], v[118:119] op_sel_hi:[1,0]
	v_pk_mul_f32 v[14:15], v[14:15], v[118:119] op_sel_hi:[1,0]
	v_pk_mul_f32 v[12:13], v[12:13], v[118:119] op_sel_hi:[1,0]
	v_pk_mul_f32 v[10:11], v[10:11], v[118:119] op_sel_hi:[1,0]
	v_pk_mul_f32 v[8:9], v[8:9], v[118:119] op_sel_hi:[1,0]
	v_pk_mul_f32 v[6:7], v[6:7], v[118:119] op_sel_hi:[1,0]
	v_pk_mul_f32 v[4:5], v[4:5], v[118:119] op_sel_hi:[1,0]
	v_pk_mul_f32 v[2:3], v[2:3], v[118:119] op_sel_hi:[1,0]
	v_add_f32_e32 v139, v127, v224
	v_add_f32_e32 v141, v123, v225
	v_add_f32_e32 v145, v124, v132
	v_add_f32_e32 v171, v125, v133
	v_add_f32_e32 v197, v128, v134
	v_add_f32_e32 v201, v129, v135
	v_add_f32_e32 v205, v130, v136
	v_add_f32_e32 v221, v131, v137
	v_cvt_pk_bf16_f32 v122, v127, v138
	v_cvt_pk_bf16_f32 v123, v123, v140
	v_cvt_pk_bf16_f32 v124, v124, v144
	v_cvt_pk_bf16_f32 v125, v125, v170
	v_cvt_pk_bf16_f32 v126, v128, v196
	v_cvt_pk_bf16_f32 v127, v129, v200
	v_cvt_pk_bf16_f32 v128, v130, v204
	v_cvt_pk_bf16_f32 v129, v131, v220
	v_cvt_pk_bf16_f32 v130, v224, v0
	v_cvt_pk_bf16_f32 v131, v225, v142
	v_cvt_pk_bf16_f32 v132, v132, v168
	v_cvt_pk_bf16_f32 v133, v133, v194
	v_cvt_pk_bf16_f32 v134, v134, v198
	v_cvt_pk_bf16_f32 v135, v135, v202
	v_cvt_pk_bf16_f32 v136, v136, v206
	v_cvt_pk_bf16_f32 v137, v137, v222
	s_waitcnt lgkmcnt(5)
	v_mfma_f32_32x32x16_bf16 v[34:49], v[86:89], v[122:125], v[34:49]
	s_waitcnt lgkmcnt(4)
	v_mfma_f32_32x32x16_bf16 v[34:49], v[82:85], v[126:129], v[34:49]
	v_add_f32_e64 v82, v138, v0
	v_add_f32_e64 v83, v139, v1
	s_waitcnt lgkmcnt(3)
	v_mfma_f32_32x32x16_bf16 v[18:33], v[78:81], v[122:125], v[18:33]
	v_add_f32_e64 v78, v82, v82
	v_add_f32_e64 v79, v82, v83
	v_mov_b32_e32 v143, v79
	v_add_f32_e64 v78, v140, v142
	v_add_f32_e64 v79, v141, v143
	v_pk_add_f32 v[78:79], v[78:79], v[78:79] op_sel_hi:[0,1]
	v_mov_b32_e32 v169, v79
	v_pk_add_f32 v[78:79], v[144:145], v[168:169]
	v_mfma_f32_32x32x16_bf16 v[50:65], v[94:97], v[122:125], v[50:65]
	v_pk_add_f32 v[78:79], v[78:79], v[78:79] op_sel_hi:[0,1]
	v_mov_b32_e32 v195, v79
	s_waitcnt lgkmcnt(1)
	v_mfma_f32_32x32x16_bf16 v[2:17], v[70:73], v[122:125], v[2:17]
	v_mfma_f32_32x32x16_bf16 v[18:33], v[74:77], v[126:129], v[18:33]
	v_add_f32_e64 v74, v170, v194
	v_add_f32_e64 v75, v171, v195
	v_pk_add_f32 v[74:75], v[74:75], v[74:75] op_sel_hi:[0,1]
	v_mov_b32_e32 v199, v75
	v_pk_add_f32 v[74:75], v[196:197], v[198:199]
	s_nop 0
	v_pk_add_f32 v[74:75], v[74:75], v[74:75] op_sel_hi:[0,1]
	v_mov_b32_e32 v203, v75
	v_mfma_f32_32x32x16_bf16 v[50:65], v[90:93], v[126:129], v[50:65]
	v_add_f32_e64 v70, v200, v202
	v_add_f32_e64 v71, v201, v203
	v_pk_add_f32 v[70:71], v[70:71], v[70:71] op_sel_hi:[0,1]
	v_mov_b32_e32 v207, v71
	v_pk_add_f32 v[70:71], v[204:205], v[206:207]
	s_nop 0
	v_pk_add_f32 v[70:71], v[70:71], v[70:71] op_sel_hi:[0,1]
	s_waitcnt lgkmcnt(0)
	v_mfma_f32_32x32x16_bf16 v[2:17], v[66:69], v[126:129], v[2:17]
	v_mov_b32_e32 v223, v71
	v_add_f32_e64 v70, v220, v222
	v_add_f32_e64 v71, v221, v223
	v_add_f32_e32 v159, v70, v71
	ds_read_b128 v[66:69], v191 offset:17472
	ds_read_b128 v[70:73], v191 offset:17504
	ds_read_b128 v[78:81], v191 offset:22080
	ds_read_b128 v[82:85], v191 offset:22112
	ds_read_b128 v[86:89], v191 offset:26688
	ds_read_b128 v[90:93], v191 offset:26720
	ds_read_b128 v[94:97], v191 offset:31296
	ds_read_b128 v[74:77], v191 offset:31328
	s_add_i32 s25, s25, 1
	s_bitcmp1_b32 s25, 0
	s_cselect_b32 s2, 0x8c00, 0
	s_add_i32 s2, s2, 0
	v_add_u32_e32 v0, s2, v167
	v_add_u32_e32 v223, s2, v208
	v_fmac_f32_e32 v159, v121, v118
	s_cmp_eq_u32 s1, s25
	s_mov_b32 s16, s14
	s_waitcnt vmcnt(3)
	ds_write_b128 v0, v[98:101]
	s_waitcnt vmcnt(1)
	ds_write_b128 v223, v[110:113] offset:17408
	ds_write_b128 v0, v[102:105] offset:8704
	s_waitcnt vmcnt(0)
	ds_write_b128 v223, v[106:109] offset:26624
	s_waitcnt lgkmcnt(11)
	v_mfma_f32_32x32x16_bf16 v[50:65], v[66:69], v[130:133], v[50:65]
	s_waitcnt lgkmcnt(10)
	v_mfma_f32_32x32x16_bf16 v[50:65], v[70:73], v[134:137], v[50:65]
	s_waitcnt lgkmcnt(9)
	v_mfma_f32_32x32x16_bf16 v[34:49], v[78:81], v[130:133], v[34:49]
	s_waitcnt lgkmcnt(8)
	v_mfma_f32_32x32x16_bf16 v[34:49], v[82:85], v[134:137], v[34:49]
	s_waitcnt lgkmcnt(7)
	v_mfma_f32_32x32x16_bf16 v[18:33], v[86:89], v[130:133], v[18:33]
	s_waitcnt lgkmcnt(6)
	v_mfma_f32_32x32x16_bf16 v[18:33], v[90:93], v[134:137], v[18:33]
	s_waitcnt lgkmcnt(5)
	v_mfma_f32_32x32x16_bf16 v[2:17], v[94:97], v[130:133], v[2:17]
	s_waitcnt lgkmcnt(0)
	s_barrier
	v_mfma_f32_32x32x16_bf16 v[2:17], v[74:77], v[134:137], v[2:17]
	s_cbranch_scc0 .LBB0_424
	s_branch .LBB0_427
